# phase E: wide branch epilogue with a pad between the last swap and the store + LDS-resident gates
# speedup vs baseline: 1.0087x; 1.0084x over previous
; __device__ __forceinline__ float bflo(unsigned u) { return __uint_as_float(u << 16); }
; __device__ __forceinline__ float bfhi(unsigned u) { return __uint_as_float(u & 0xFFFF0000u); }
; __device__ __forceinline__ void phaseE(const Params& p, int layer) {
;     ...
;               uint4 g4[2]; uint2 old[2][2];
; #pragma unroll
;               for (int mm = 0; mm < 2; mm++) {
;                 const int m = mh * 2 + mm;
;                 g4[mm] = *(const uint4*)(gsb + ((ai * 2 + bj) * 4 + m) * 8192 + gs_lane);
;                 if (br) {
; #pragma unroll
;                   for (int n = 0; n < 2; n++)
;                     old[mm][n] = *(const uint2*)(mb + ((size_t)(ai * 128 + m * 16) * 2048 + bj * 128 + n * 16) * 2 + lane_m);
;                 }
;               }
; #pragma unroll
;               for (int mm = 0; mm < 2; mm++) {
;                 const int m = mh * 2 + mm;
;                 const unsigned gq[4] = {g4[mm].x, g4[mm].y, g4[mm].z, g4[mm].w};
; #pragma unroll
;                 for (int n = 0; n < 2; n++) {
;                   f32x4 v = acc[ai][bj][m][n];
;                   float o0 = bflo(gq[2 * n]) * v[0], o1 = bfhi(gq[2 * n]) * v[1], o2 = bflo(gq[2 * n + 1]) * v[2], o3 = bfhi(gq[2 * n + 1]) * v[3];
;                   char* mp = mb + ((size_t)(ai * 128 + m * 16) * 2048 + bj * 128 + n * 16) * 2 + lane_m;
;                   if (br) { o0 += bflo(old[mm][n].x); o1 += bfhi(old[mm][n].x); o2 += bflo(old[mm][n].y); o3 += bfhi(old[mm][n].y); }
;                   *(uint2*)mp = make_uint2(pk2(o0, o1), pk2(o2, o3));
;                 }
;               }
.LBB0_2323:
	v_readlane_b32 s0, v253, 51
	v_readlane_b32 s1, v253, 52
	v_add_u32_e32 v165, 0x20000, v160
	v_and_b32_e32 v163, 63, v162
	v_add_u32_e32 v163, v163, v162
	s_cmp_lg_u64 s[12:13], 0
	s_nop 3
	s_cbranch_scc0 .Lbrepi_first
	ds_read_b128 v[128:131], v165
	global_load_dwordx4 v[132:135], v163, s[6:7]
	ds_read_b128 v[136:139], v165 offset:8192
	v_add_u32_e32 v210, 0x10000, v163
	global_load_dwordx4 v[140:143], v210, s[6:7]
	ds_read_b128 v[148:151], v165 offset:16384
	v_add_u32_e32 v211, 0x20000, v163
	global_load_dwordx4 v[152:155], v211, s[6:7]
	ds_read_b128 v[164:167], v165 offset:24576
	v_add_u32_e32 v210, 0x30000, v163
	global_load_dwordx4 v[168:171], v210, s[6:7]
	v_add_u32_e32 v146, 0x8000, v160
	global_load_dwordx4 v[172:175], v146, s[0:1]
	global_load_dwordx4 v[176:179], v163, s[6:7] offset:256
	v_add_u32_e32 v147, 0xa000, v160
	global_load_dwordx4 v[180:183], v147, s[0:1]
	v_add_u32_e32 v211, 0x10000, v163
	global_load_dwordx4 v[184:187], v211, s[6:7] offset:256
	v_add_u32_e32 v146, 0xc000, v160
	global_load_dwordx4 v[188:191], v146, s[0:1]
	v_add_u32_e32 v210, 0x20000, v163
	global_load_dwordx4 v[192:195], v210, s[6:7] offset:256
	v_add_u32_e32 v147, 0xe000, v160
	global_load_dwordx4 v[212:215], v147, s[0:1]
	v_add_u32_e32 v211, 0x30000, v163
	global_load_dwordx4 v[216:219], v211, s[6:7] offset:256
	v_add_u32_e32 v146, 0x10000, v160
	global_load_dwordx4 v[220:223], v146, s[0:1]
	v_add_u32_e32 v210, 0x80000, v163
	global_load_dwordx4 v[224:227], v210, s[6:7]
	v_add_u32_e32 v147, 0x12000, v160
	global_load_dwordx4 v[228:231], v147, s[0:1]
	v_add_u32_e32 v211, 0x90000, v163
	global_load_dwordx4 v[232:235], v211, s[6:7]
	v_add_u32_e32 v146, 0x14000, v160
	global_load_dwordx4 v[236:239], v146, s[0:1]
	v_add_u32_e32 v210, 0xa0000, v163
	global_load_dwordx4 v[240:243], v210, s[6:7]
	s_waitcnt vmcnt(17) lgkmcnt(0)
	v_permlane16_swap_b32_e32 v132, v134
	v_permlane16_swap_b32_e32 v133, v135
	v_lshlrev_b32_e32 v156, 16, v128
	v_and_b32_e32 v157, 0xffff0000, v128
	v_lshlrev_b32_e32 v158, 16, v129
	v_and_b32_e32 v159, 0xffff0000, v129
	v_pk_mul_f32 v[156:157], v[124:125], v[156:157]
	v_pk_mul_f32 v[158:159], v[126:127], v[158:159]
	v_permlane32_swap_b32_e32 v132, v134
	v_permlane32_swap_b32_e32 v133, v135
	v_lshlrev_b32_e32 v244, 16, v130
	v_and_b32_e32 v245, 0xffff0000, v130
	v_lshlrev_b32_e32 v246, 16, v131
	v_and_b32_e32 v247, 0xffff0000, v131
	v_pk_mul_f32 v[244:245], v[120:121], v[244:245]
	v_pk_mul_f32 v[246:247], v[122:123], v[246:247]
	v_lshlrev_b32_e32 v196, 16, v132
	v_and_b32_e32 v197, 0xffff0000, v132
	v_lshlrev_b32_e32 v198, 16, v133
	v_and_b32_e32 v199, 0xffff0000, v133
	v_pk_add_f32 v[156:157], v[156:157], v[196:197]
	v_pk_add_f32 v[158:159], v[158:159], v[198:199]
	v_lshlrev_b32_e32 v200, 16, v134
	v_and_b32_e32 v201, 0xffff0000, v134
	v_lshlrev_b32_e32 v204, 16, v135
	v_and_b32_e32 v205, 0xffff0000, v135
	v_pk_add_f32 v[244:245], v[244:245], v[200:201]
	v_pk_add_f32 v[246:247], v[246:247], v[204:205]
	v_cvt_pk_bf16_f32 v156, v156, v157
	v_cvt_pk_bf16_f32 v157, v158, v159
	v_cvt_pk_bf16_f32 v158, v244, v245
	v_cvt_pk_bf16_f32 v159, v246, v247
	s_nop 1
	v_permlane32_swap_b32_e32 v156, v158
	v_permlane32_swap_b32_e32 v157, v159
	s_nop 0
	v_permlane16_swap_b32_e32 v156, v158
	v_permlane16_swap_b32_e32 v157, v159
	s_nop 1
	global_store_dwordx4 v163, v[156:159], s[6:7]
	v_add_u32_e32 v147, 0x16000, v160
	global_load_dwordx4 v[128:131], v147, s[0:1]
	v_add_u32_e32 v211, 0xb0000, v163
	global_load_dwordx4 v[132:135], v211, s[6:7]
	s_waitcnt vmcnt(19) lgkmcnt(0)
	v_permlane16_swap_b32_e32 v140, v142
	v_permlane16_swap_b32_e32 v141, v143
	v_lshlrev_b32_e32 v156, 16, v136
	v_and_b32_e32 v157, 0xffff0000, v136
	v_lshlrev_b32_e32 v158, 16, v137
	v_and_b32_e32 v159, 0xffff0000, v137
	v_pk_mul_f32 v[156:157], v[116:117], v[156:157]
	v_pk_mul_f32 v[158:159], v[118:119], v[158:159]
	v_permlane32_swap_b32_e32 v140, v142
	v_permlane32_swap_b32_e32 v141, v143
	v_lshlrev_b32_e32 v244, 16, v138
	v_and_b32_e32 v245, 0xffff0000, v138
	v_lshlrev_b32_e32 v246, 16, v139
	v_and_b32_e32 v247, 0xffff0000, v139
	v_pk_mul_f32 v[244:245], v[112:113], v[244:245]
	v_pk_mul_f32 v[246:247], v[114:115], v[246:247]
	v_lshlrev_b32_e32 v196, 16, v140
	v_and_b32_e32 v197, 0xffff0000, v140
	v_lshlrev_b32_e32 v198, 16, v141
	v_and_b32_e32 v199, 0xffff0000, v141
	v_pk_add_f32 v[156:157], v[156:157], v[196:197]
	v_pk_add_f32 v[158:159], v[158:159], v[198:199]
	v_lshlrev_b32_e32 v200, 16, v142
	v_and_b32_e32 v201, 0xffff0000, v142
	v_lshlrev_b32_e32 v204, 16, v143
	v_and_b32_e32 v205, 0xffff0000, v143
	v_pk_add_f32 v[244:245], v[244:245], v[200:201]
	v_pk_add_f32 v[246:247], v[246:247], v[204:205]
	v_cvt_pk_bf16_f32 v156, v156, v157
	v_cvt_pk_bf16_f32 v157, v158, v159
	v_cvt_pk_bf16_f32 v158, v244, v245
	v_cvt_pk_bf16_f32 v159, v246, v247
	v_add_u32_e32 v210, 0x10000, v163
	s_nop 1
	v_permlane32_swap_b32_e32 v156, v158
	v_permlane32_swap_b32_e32 v157, v159
	s_nop 0
	v_permlane16_swap_b32_e32 v156, v158
	v_permlane16_swap_b32_e32 v157, v159
	s_nop 1
	global_store_dwordx4 v210, v[156:159], s[6:7]
	v_add_u32_e32 v146, 0x18000, v160
	global_load_dwordx4 v[136:139], v146, s[0:1]
	v_add_u32_e32 v211, 0x80000, v163
	global_load_dwordx4 v[140:143], v211, s[6:7] offset:256
	s_waitcnt vmcnt(21) lgkmcnt(0)
; __device__ __forceinline__ float bflo(unsigned u) { return __uint_as_float(u << 16); }
; __device__ __forceinline__ float bfhi(unsigned u) { return __uint_as_float(u & 0xFFFF0000u); }
; __device__ __forceinline__ void phaseE(const Params& p, int layer) {
;     ...
;               uint4 g4[2]; uint2 old[2][2];
; #pragma unroll
;               for (int mm = 0; mm < 2; mm++) {
;                 const int m = mh * 2 + mm;
;                 g4[mm] = *(const uint4*)(gsb + ((ai * 2 + bj) * 4 + m) * 8192 + gs_lane);
;                 if (br) {
; #pragma unroll
;                   for (int n = 0; n < 2; n++)
;                     old[mm][n] = *(const uint2*)(mb + ((size_t)(ai * 128 + m * 16) * 2048 + bj * 128 + n * 16) * 2 + lane_m);
;                 }
;               }
; #pragma unroll
;               for (int mm = 0; mm < 2; mm++) {
;                 const int m = mh * 2 + mm;
;                 const unsigned gq[4] = {g4[mm].x, g4[mm].y, g4[mm].z, g4[mm].w};
; #pragma unroll
;                 for (int n = 0; n < 2; n++) {
;                   f32x4 v = acc[ai][bj][m][n];
;                   float o0 = bflo(gq[2 * n]) * v[0], o1 = bfhi(gq[2 * n]) * v[1], o2 = bflo(gq[2 * n + 1]) * v[2], o3 = bfhi(gq[2 * n + 1]) * v[3];
;                   char* mp = mb + ((size_t)(ai * 128 + m * 16) * 2048 + bj * 128 + n * 16) * 2 + lane_m;
;                   if (br) { o0 += bflo(old[mm][n].x); o1 += bfhi(old[mm][n].x); o2 += bflo(old[mm][n].y); o3 += bfhi(old[mm][n].y); }
;                   *(uint2*)mp = make_uint2(pk2(o0, o1), pk2(o2, o3));
;                 }
;               }
	v_permlane16_swap_b32_e32 v152, v154
	v_permlane16_swap_b32_e32 v153, v155
	v_lshlrev_b32_e32 v156, 16, v148
	v_and_b32_e32 v157, 0xffff0000, v148
	v_lshlrev_b32_e32 v158, 16, v149
	v_and_b32_e32 v159, 0xffff0000, v149
	v_pk_mul_f32 v[156:157], v[108:109], v[156:157]
	v_pk_mul_f32 v[158:159], v[110:111], v[158:159]
	v_permlane32_swap_b32_e32 v152, v154
	v_permlane32_swap_b32_e32 v153, v155
	v_lshlrev_b32_e32 v244, 16, v150
	v_and_b32_e32 v245, 0xffff0000, v150
	v_lshlrev_b32_e32 v246, 16, v151
	v_and_b32_e32 v247, 0xffff0000, v151
	v_pk_mul_f32 v[244:245], v[104:105], v[244:245]
	v_pk_mul_f32 v[246:247], v[106:107], v[246:247]
	v_lshlrev_b32_e32 v196, 16, v152
	v_and_b32_e32 v197, 0xffff0000, v152
	v_lshlrev_b32_e32 v198, 16, v153
	v_and_b32_e32 v199, 0xffff0000, v153
	v_pk_add_f32 v[156:157], v[156:157], v[196:197]
	v_pk_add_f32 v[158:159], v[158:159], v[198:199]
	v_lshlrev_b32_e32 v200, 16, v154
	v_and_b32_e32 v201, 0xffff0000, v154
	v_lshlrev_b32_e32 v204, 16, v155
	v_and_b32_e32 v205, 0xffff0000, v155
	v_pk_add_f32 v[244:245], v[244:245], v[200:201]
	v_pk_add_f32 v[246:247], v[246:247], v[204:205]
	v_cvt_pk_bf16_f32 v156, v156, v157
	v_cvt_pk_bf16_f32 v157, v158, v159
	v_cvt_pk_bf16_f32 v158, v244, v245
	v_cvt_pk_bf16_f32 v159, v246, v247
	v_add_u32_e32 v210, 0x20000, v163
	s_nop 1
	v_permlane32_swap_b32_e32 v156, v158
	v_permlane32_swap_b32_e32 v157, v159
	s_nop 0
	v_permlane16_swap_b32_e32 v156, v158
	v_permlane16_swap_b32_e32 v157, v159
	s_nop 1
	global_store_dwordx4 v210, v[156:159], s[6:7]
	v_add_u32_e32 v147, 0x1a000, v160
	global_load_dwordx4 v[148:151], v147, s[0:1]
	v_add_u32_e32 v211, 0x90000, v163
	global_load_dwordx4 v[152:155], v211, s[6:7] offset:256
	s_waitcnt vmcnt(23) lgkmcnt(0)
	v_permlane16_swap_b32_e32 v168, v170
	v_permlane16_swap_b32_e32 v169, v171
	v_lshlrev_b32_e32 v156, 16, v164
	v_and_b32_e32 v157, 0xffff0000, v164
	v_lshlrev_b32_e32 v158, 16, v165
	v_and_b32_e32 v159, 0xffff0000, v165
	v_pk_mul_f32 v[156:157], v[100:101], v[156:157]
	v_pk_mul_f32 v[158:159], v[102:103], v[158:159]
	v_permlane32_swap_b32_e32 v168, v170
	v_permlane32_swap_b32_e32 v169, v171
	v_lshlrev_b32_e32 v244, 16, v166
	v_and_b32_e32 v245, 0xffff0000, v166
	v_lshlrev_b32_e32 v246, 16, v167
	v_and_b32_e32 v247, 0xffff0000, v167
	v_pk_mul_f32 v[244:245], v[96:97], v[244:245]
	v_pk_mul_f32 v[246:247], v[98:99], v[246:247]
	v_lshlrev_b32_e32 v196, 16, v168
	v_and_b32_e32 v197, 0xffff0000, v168
	v_lshlrev_b32_e32 v198, 16, v169
	v_and_b32_e32 v199, 0xffff0000, v169
	v_pk_add_f32 v[156:157], v[156:157], v[196:197]
	v_pk_add_f32 v[158:159], v[158:159], v[198:199]
	v_lshlrev_b32_e32 v200, 16, v170
	v_and_b32_e32 v201, 0xffff0000, v170
	v_lshlrev_b32_e32 v204, 16, v171
	v_and_b32_e32 v205, 0xffff0000, v171
	v_pk_add_f32 v[244:245], v[244:245], v[200:201]
	v_pk_add_f32 v[246:247], v[246:247], v[204:205]
	v_cvt_pk_bf16_f32 v156, v156, v157
	v_cvt_pk_bf16_f32 v157, v158, v159
	v_cvt_pk_bf16_f32 v158, v244, v245
	v_cvt_pk_bf16_f32 v159, v246, v247
	v_add_u32_e32 v210, 0x30000, v163
	s_nop 1
	v_permlane32_swap_b32_e32 v156, v158
	v_permlane32_swap_b32_e32 v157, v159
	s_nop 0
	v_permlane16_swap_b32_e32 v156, v158
	v_permlane16_swap_b32_e32 v157, v159
	s_nop 1
	global_store_dwordx4 v210, v[156:159], s[6:7]
	v_add_u32_e32 v146, 0x1c000, v160
	global_load_dwordx4 v[164:167], v146, s[0:1]
	v_add_u32_e32 v211, 0xa0000, v163
	global_load_dwordx4 v[168:171], v211, s[6:7] offset:256
	s_waitcnt vmcnt(24)
	v_permlane16_swap_b32_e32 v176, v178
	v_permlane16_swap_b32_e32 v177, v179
	v_lshlrev_b32_e32 v156, 16, v172
	v_and_b32_e32 v157, 0xffff0000, v172
	v_lshlrev_b32_e32 v158, 16, v173
	v_and_b32_e32 v159, 0xffff0000, v173
	v_pk_mul_f32 v[156:157], v[92:93], v[156:157]
	v_pk_mul_f32 v[158:159], v[94:95], v[158:159]
	v_permlane32_swap_b32_e32 v176, v178
	v_permlane32_swap_b32_e32 v177, v179
	v_lshlrev_b32_e32 v244, 16, v174
	v_and_b32_e32 v245, 0xffff0000, v174
	v_lshlrev_b32_e32 v246, 16, v175
	v_and_b32_e32 v247, 0xffff0000, v175
	v_pk_mul_f32 v[244:245], v[88:89], v[244:245]
	v_pk_mul_f32 v[246:247], v[90:91], v[246:247]
	v_lshlrev_b32_e32 v196, 16, v176
	v_and_b32_e32 v197, 0xffff0000, v176
	v_lshlrev_b32_e32 v198, 16, v177
	v_and_b32_e32 v199, 0xffff0000, v177
	v_pk_add_f32 v[156:157], v[156:157], v[196:197]
	v_pk_add_f32 v[158:159], v[158:159], v[198:199]
	v_lshlrev_b32_e32 v200, 16, v178
	v_and_b32_e32 v201, 0xffff0000, v178
	v_lshlrev_b32_e32 v204, 16, v179
	v_and_b32_e32 v205, 0xffff0000, v179
	v_pk_add_f32 v[244:245], v[244:245], v[200:201]
	v_pk_add_f32 v[246:247], v[246:247], v[204:205]
	v_cvt_pk_bf16_f32 v156, v156, v157
	v_cvt_pk_bf16_f32 v157, v158, v159
	v_cvt_pk_bf16_f32 v158, v244, v245
	v_cvt_pk_bf16_f32 v159, v246, v247
	s_nop 1
	v_permlane32_swap_b32_e32 v156, v158
	v_permlane32_swap_b32_e32 v157, v159
	s_nop 0
	v_permlane16_swap_b32_e32 v156, v158
	v_permlane16_swap_b32_e32 v157, v159
	s_nop 1
	global_store_dwordx4 v163, v[156:159], s[6:7] offset:256
	v_add_u32_e32 v147, 0x1e000, v160
	global_load_dwordx4 v[172:175], v147, s[0:1]
	v_add_u32_e32 v210, 0xb0000, v163
	global_load_dwordx4 v[176:179], v210, s[6:7] offset:256
	s_waitcnt vmcnt(25)
; __device__ __forceinline__ float bflo(unsigned u) { return __uint_as_float(u << 16); }
; __device__ __forceinline__ float bfhi(unsigned u) { return __uint_as_float(u & 0xFFFF0000u); }
; __device__ __forceinline__ void phaseE(const Params& p, int layer) {
;     ...
;               uint4 g4[2]; uint2 old[2][2];
; #pragma unroll
;               for (int mm = 0; mm < 2; mm++) {
;                 const int m = mh * 2 + mm;
;                 g4[mm] = *(const uint4*)(gsb + ((ai * 2 + bj) * 4 + m) * 8192 + gs_lane);
;                 if (br) {
; #pragma unroll
;                   for (int n = 0; n < 2; n++)
;                     old[mm][n] = *(const uint2*)(mb + ((size_t)(ai * 128 + m * 16) * 2048 + bj * 128 + n * 16) * 2 + lane_m);
;                 }
;               }
; #pragma unroll
;               for (int mm = 0; mm < 2; mm++) {
;                 const int m = mh * 2 + mm;
;                 const unsigned gq[4] = {g4[mm].x, g4[mm].y, g4[mm].z, g4[mm].w};
; #pragma unroll
;                 for (int n = 0; n < 2; n++) {
;                   f32x4 v = acc[ai][bj][m][n];
;                   float o0 = bflo(gq[2 * n]) * v[0], o1 = bfhi(gq[2 * n]) * v[1], o2 = bflo(gq[2 * n + 1]) * v[2], o3 = bfhi(gq[2 * n + 1]) * v[3];
;                   char* mp = mb + ((size_t)(ai * 128 + m * 16) * 2048 + bj * 128 + n * 16) * 2 + lane_m;
;                   if (br) { o0 += bflo(old[mm][n].x); o1 += bfhi(old[mm][n].x); o2 += bflo(old[mm][n].y); o3 += bfhi(old[mm][n].y); }
;                   *(uint2*)mp = make_uint2(pk2(o0, o1), pk2(o2, o3));
;                 }
;               }
	v_permlane16_swap_b32_e32 v184, v186
	v_permlane16_swap_b32_e32 v185, v187
	v_lshlrev_b32_e32 v156, 16, v180
	v_and_b32_e32 v157, 0xffff0000, v180
	v_lshlrev_b32_e32 v158, 16, v181
	v_and_b32_e32 v159, 0xffff0000, v181
	v_pk_mul_f32 v[156:157], v[84:85], v[156:157]
	v_pk_mul_f32 v[158:159], v[86:87], v[158:159]
	v_permlane32_swap_b32_e32 v184, v186
	v_permlane32_swap_b32_e32 v185, v187
	v_lshlrev_b32_e32 v244, 16, v182
	v_and_b32_e32 v245, 0xffff0000, v182
	v_lshlrev_b32_e32 v246, 16, v183
	v_and_b32_e32 v247, 0xffff0000, v183
	v_pk_mul_f32 v[244:245], v[80:81], v[244:245]
	v_pk_mul_f32 v[246:247], v[82:83], v[246:247]
	v_lshlrev_b32_e32 v196, 16, v184
	v_and_b32_e32 v197, 0xffff0000, v184
	v_lshlrev_b32_e32 v198, 16, v185
	v_and_b32_e32 v199, 0xffff0000, v185
	v_pk_add_f32 v[156:157], v[156:157], v[196:197]
	v_pk_add_f32 v[158:159], v[158:159], v[198:199]
	v_lshlrev_b32_e32 v200, 16, v186
	v_and_b32_e32 v201, 0xffff0000, v186
	v_lshlrev_b32_e32 v204, 16, v187
	v_and_b32_e32 v205, 0xffff0000, v187
	v_pk_add_f32 v[244:245], v[244:245], v[200:201]
	v_pk_add_f32 v[246:247], v[246:247], v[204:205]
	v_cvt_pk_bf16_f32 v156, v156, v157
	v_cvt_pk_bf16_f32 v157, v158, v159
	v_cvt_pk_bf16_f32 v158, v244, v245
	v_cvt_pk_bf16_f32 v159, v246, v247
	v_add_u32_e32 v211, 0x10000, v163
	s_nop 1
	v_permlane32_swap_b32_e32 v156, v158
	v_permlane32_swap_b32_e32 v157, v159
	s_nop 0
	v_permlane16_swap_b32_e32 v156, v158
	v_permlane16_swap_b32_e32 v157, v159
	s_nop 1
	global_store_dwordx4 v211, v[156:159], s[6:7] offset:256
	s_waitcnt vmcnt(24)
	v_permlane16_swap_b32_e32 v192, v194
	v_permlane16_swap_b32_e32 v193, v195
	v_lshlrev_b32_e32 v156, 16, v188
	v_and_b32_e32 v157, 0xffff0000, v188
	v_lshlrev_b32_e32 v158, 16, v189
	v_and_b32_e32 v159, 0xffff0000, v189
	v_pk_mul_f32 v[156:157], v[76:77], v[156:157]
	v_pk_mul_f32 v[158:159], v[78:79], v[158:159]
	v_permlane32_swap_b32_e32 v192, v194
	v_permlane32_swap_b32_e32 v193, v195
	v_lshlrev_b32_e32 v244, 16, v190
	v_and_b32_e32 v245, 0xffff0000, v190
	v_lshlrev_b32_e32 v246, 16, v191
	v_and_b32_e32 v247, 0xffff0000, v191
	v_pk_mul_f32 v[244:245], v[72:73], v[244:245]
	v_pk_mul_f32 v[246:247], v[74:75], v[246:247]
	v_lshlrev_b32_e32 v196, 16, v192
	v_and_b32_e32 v197, 0xffff0000, v192
	v_lshlrev_b32_e32 v198, 16, v193
	v_and_b32_e32 v199, 0xffff0000, v193
	v_pk_add_f32 v[156:157], v[156:157], v[196:197]
	v_pk_add_f32 v[158:159], v[158:159], v[198:199]
	v_lshlrev_b32_e32 v200, 16, v194
	v_and_b32_e32 v201, 0xffff0000, v194
	v_lshlrev_b32_e32 v204, 16, v195
	v_and_b32_e32 v205, 0xffff0000, v195
	v_pk_add_f32 v[244:245], v[244:245], v[200:201]
	v_pk_add_f32 v[246:247], v[246:247], v[204:205]
	v_cvt_pk_bf16_f32 v156, v156, v157
	v_cvt_pk_bf16_f32 v157, v158, v159
	v_cvt_pk_bf16_f32 v158, v244, v245
	v_cvt_pk_bf16_f32 v159, v246, v247
	v_add_u32_e32 v210, 0x20000, v163
	s_nop 1
	v_permlane32_swap_b32_e32 v156, v158
	v_permlane32_swap_b32_e32 v157, v159
	s_nop 0
	v_permlane16_swap_b32_e32 v156, v158
	v_permlane16_swap_b32_e32 v157, v159
	s_nop 1
	global_store_dwordx4 v210, v[156:159], s[6:7] offset:256
	s_waitcnt vmcnt(23)
	v_permlane16_swap_b32_e32 v216, v218
	v_permlane16_swap_b32_e32 v217, v219
	v_lshlrev_b32_e32 v156, 16, v212
	v_and_b32_e32 v157, 0xffff0000, v212
	v_lshlrev_b32_e32 v158, 16, v213
	v_and_b32_e32 v159, 0xffff0000, v213
	v_pk_mul_f32 v[156:157], v[68:69], v[156:157]
	v_pk_mul_f32 v[158:159], v[70:71], v[158:159]
	v_permlane32_swap_b32_e32 v216, v218
	v_permlane32_swap_b32_e32 v217, v219
	v_lshlrev_b32_e32 v244, 16, v214
	v_and_b32_e32 v245, 0xffff0000, v214
	v_lshlrev_b32_e32 v246, 16, v215
	v_and_b32_e32 v247, 0xffff0000, v215
	v_pk_mul_f32 v[244:245], v[64:65], v[244:245]
	v_pk_mul_f32 v[246:247], v[66:67], v[246:247]
	v_lshlrev_b32_e32 v196, 16, v216
	v_and_b32_e32 v197, 0xffff0000, v216
	v_lshlrev_b32_e32 v198, 16, v217
	v_and_b32_e32 v199, 0xffff0000, v217
	v_pk_add_f32 v[156:157], v[156:157], v[196:197]
	v_pk_add_f32 v[158:159], v[158:159], v[198:199]
	v_lshlrev_b32_e32 v200, 16, v218
	v_and_b32_e32 v201, 0xffff0000, v218
	v_lshlrev_b32_e32 v204, 16, v219
	v_and_b32_e32 v205, 0xffff0000, v219
	v_pk_add_f32 v[244:245], v[244:245], v[200:201]
	v_pk_add_f32 v[246:247], v[246:247], v[204:205]
	v_cvt_pk_bf16_f32 v156, v156, v157
	v_cvt_pk_bf16_f32 v157, v158, v159
	v_cvt_pk_bf16_f32 v158, v244, v245
	v_cvt_pk_bf16_f32 v159, v246, v247
	v_add_u32_e32 v211, 0x30000, v163
	s_nop 1
	v_permlane32_swap_b32_e32 v156, v158
	v_permlane32_swap_b32_e32 v157, v159
	s_nop 0
	v_permlane16_swap_b32_e32 v156, v158
	v_permlane16_swap_b32_e32 v157, v159
	s_nop 1
	global_store_dwordx4 v211, v[156:159], s[6:7] offset:256
	s_waitcnt vmcnt(22)
	v_permlane16_swap_b32_e32 v224, v226
	v_permlane16_swap_b32_e32 v225, v227
	v_lshlrev_b32_e32 v156, 16, v220
	v_and_b32_e32 v157, 0xffff0000, v220
	v_lshlrev_b32_e32 v158, 16, v221
	v_and_b32_e32 v159, 0xffff0000, v221
	v_pk_mul_f32 v[156:157], v[60:61], v[156:157]
	v_pk_mul_f32 v[158:159], v[62:63], v[158:159]
	v_permlane32_swap_b32_e32 v224, v226
	v_permlane32_swap_b32_e32 v225, v227
	v_lshlrev_b32_e32 v244, 16, v222
	v_and_b32_e32 v245, 0xffff0000, v222
	v_lshlrev_b32_e32 v246, 16, v223
	v_and_b32_e32 v247, 0xffff0000, v223
	v_pk_mul_f32 v[244:245], v[56:57], v[244:245]
	v_pk_mul_f32 v[246:247], v[58:59], v[246:247]
	v_lshlrev_b32_e32 v196, 16, v224
	v_and_b32_e32 v197, 0xffff0000, v224
	v_lshlrev_b32_e32 v198, 16, v225
	v_and_b32_e32 v199, 0xffff0000, v225
	v_pk_add_f32 v[156:157], v[156:157], v[196:197]
	v_pk_add_f32 v[158:159], v[158:159], v[198:199]
	v_lshlrev_b32_e32 v200, 16, v226
	v_and_b32_e32 v201, 0xffff0000, v226
	v_lshlrev_b32_e32 v204, 16, v227
	v_and_b32_e32 v205, 0xffff0000, v227
	v_pk_add_f32 v[244:245], v[244:245], v[200:201]
	v_pk_add_f32 v[246:247], v[246:247], v[204:205]
	v_cvt_pk_bf16_f32 v156, v156, v157
	v_cvt_pk_bf16_f32 v157, v158, v159
	v_cvt_pk_bf16_f32 v158, v244, v245
	v_cvt_pk_bf16_f32 v159, v246, v247
	v_add_u32_e32 v210, 0x80000, v163
	s_nop 1
	v_permlane32_swap_b32_e32 v156, v158
	v_permlane32_swap_b32_e32 v157, v159
	s_nop 0
	v_permlane16_swap_b32_e32 v156, v158
	v_permlane16_swap_b32_e32 v157, v159
	s_nop 1
	global_store_dwordx4 v210, v[156:159], s[6:7]
	s_waitcnt vmcnt(21)
; __device__ __forceinline__ float bflo(unsigned u) { return __uint_as_float(u << 16); }
; __device__ __forceinline__ float bfhi(unsigned u) { return __uint_as_float(u & 0xFFFF0000u); }
; __device__ __forceinline__ void phaseE(const Params& p, int layer) {
;     ...
;               uint4 g4[2]; uint2 old[2][2];
; #pragma unroll
;               for (int mm = 0; mm < 2; mm++) {
;                 const int m = mh * 2 + mm;
;                 g4[mm] = *(const uint4*)(gsb + ((ai * 2 + bj) * 4 + m) * 8192 + gs_lane);
;                 if (br) {
; #pragma unroll
;                   for (int n = 0; n < 2; n++)
;                     old[mm][n] = *(const uint2*)(mb + ((size_t)(ai * 128 + m * 16) * 2048 + bj * 128 + n * 16) * 2 + lane_m);
;                 }
;               }
; #pragma unroll
;               for (int mm = 0; mm < 2; mm++) {
;                 const int m = mh * 2 + mm;
;                 const unsigned gq[4] = {g4[mm].x, g4[mm].y, g4[mm].z, g4[mm].w};
; #pragma unroll
;                 for (int n = 0; n < 2; n++) {
;                   f32x4 v = acc[ai][bj][m][n];
;                   float o0 = bflo(gq[2 * n]) * v[0], o1 = bfhi(gq[2 * n]) * v[1], o2 = bflo(gq[2 * n + 1]) * v[2], o3 = bfhi(gq[2 * n + 1]) * v[3];
;                   char* mp = mb + ((size_t)(ai * 128 + m * 16) * 2048 + bj * 128 + n * 16) * 2 + lane_m;
;                   if (br) { o0 += bflo(old[mm][n].x); o1 += bfhi(old[mm][n].x); o2 += bflo(old[mm][n].y); o3 += bfhi(old[mm][n].y); }
;                   *(uint2*)mp = make_uint2(pk2(o0, o1), pk2(o2, o3));
;                 }
;               }
	v_permlane16_swap_b32_e32 v232, v234
	v_permlane16_swap_b32_e32 v233, v235
	v_lshlrev_b32_e32 v156, 16, v228
	v_and_b32_e32 v157, 0xffff0000, v228
	v_lshlrev_b32_e32 v158, 16, v229
	v_and_b32_e32 v159, 0xffff0000, v229
	v_pk_mul_f32 v[156:157], v[52:53], v[156:157]
	v_pk_mul_f32 v[158:159], v[54:55], v[158:159]
	v_permlane32_swap_b32_e32 v232, v234
	v_permlane32_swap_b32_e32 v233, v235
	v_lshlrev_b32_e32 v244, 16, v230
	v_and_b32_e32 v245, 0xffff0000, v230
	v_lshlrev_b32_e32 v246, 16, v231
	v_and_b32_e32 v247, 0xffff0000, v231
	v_pk_mul_f32 v[244:245], v[48:49], v[244:245]
	v_pk_mul_f32 v[246:247], v[50:51], v[246:247]
	v_lshlrev_b32_e32 v196, 16, v232
	v_and_b32_e32 v197, 0xffff0000, v232
	v_lshlrev_b32_e32 v198, 16, v233
	v_and_b32_e32 v199, 0xffff0000, v233
	v_pk_add_f32 v[156:157], v[156:157], v[196:197]
	v_pk_add_f32 v[158:159], v[158:159], v[198:199]
	v_lshlrev_b32_e32 v200, 16, v234
	v_and_b32_e32 v201, 0xffff0000, v234
	v_lshlrev_b32_e32 v204, 16, v235
	v_and_b32_e32 v205, 0xffff0000, v235
	v_pk_add_f32 v[244:245], v[244:245], v[200:201]
	v_pk_add_f32 v[246:247], v[246:247], v[204:205]
	v_cvt_pk_bf16_f32 v156, v156, v157
	v_cvt_pk_bf16_f32 v157, v158, v159
	v_cvt_pk_bf16_f32 v158, v244, v245
	v_cvt_pk_bf16_f32 v159, v246, v247
	v_add_u32_e32 v211, 0x90000, v163
	s_nop 1
	v_permlane32_swap_b32_e32 v156, v158
	v_permlane32_swap_b32_e32 v157, v159
	s_nop 0
	v_permlane16_swap_b32_e32 v156, v158
	v_permlane16_swap_b32_e32 v157, v159
	s_nop 1
	global_store_dwordx4 v211, v[156:159], s[6:7]
	s_waitcnt vmcnt(20)
	v_permlane16_swap_b32_e32 v240, v242
	v_permlane16_swap_b32_e32 v241, v243
	v_lshlrev_b32_e32 v156, 16, v236
	v_and_b32_e32 v157, 0xffff0000, v236
	v_lshlrev_b32_e32 v158, 16, v237
	v_and_b32_e32 v159, 0xffff0000, v237
	v_pk_mul_f32 v[156:157], v[44:45], v[156:157]
	v_pk_mul_f32 v[158:159], v[46:47], v[158:159]
	v_permlane32_swap_b32_e32 v240, v242
	v_permlane32_swap_b32_e32 v241, v243
	v_lshlrev_b32_e32 v244, 16, v238
	v_and_b32_e32 v245, 0xffff0000, v238
	v_lshlrev_b32_e32 v246, 16, v239
	v_and_b32_e32 v247, 0xffff0000, v239
	v_pk_mul_f32 v[244:245], v[40:41], v[244:245]
	v_pk_mul_f32 v[246:247], v[42:43], v[246:247]
	v_lshlrev_b32_e32 v196, 16, v240
	v_and_b32_e32 v197, 0xffff0000, v240
	v_lshlrev_b32_e32 v198, 16, v241
	v_and_b32_e32 v199, 0xffff0000, v241
	v_pk_add_f32 v[156:157], v[156:157], v[196:197]
	v_pk_add_f32 v[158:159], v[158:159], v[198:199]
	v_lshlrev_b32_e32 v200, 16, v242
	v_and_b32_e32 v201, 0xffff0000, v242
	v_lshlrev_b32_e32 v204, 16, v243
	v_and_b32_e32 v205, 0xffff0000, v243
	v_pk_add_f32 v[244:245], v[244:245], v[200:201]
	v_pk_add_f32 v[246:247], v[246:247], v[204:205]
	v_cvt_pk_bf16_f32 v156, v156, v157
	v_cvt_pk_bf16_f32 v157, v158, v159
	v_cvt_pk_bf16_f32 v158, v244, v245
	v_cvt_pk_bf16_f32 v159, v246, v247
	v_add_u32_e32 v210, 0xa0000, v163
	s_nop 1
	v_permlane32_swap_b32_e32 v156, v158
	v_permlane32_swap_b32_e32 v157, v159
	s_nop 0
	v_permlane16_swap_b32_e32 v156, v158
	v_permlane16_swap_b32_e32 v157, v159
	s_nop 1
	global_store_dwordx4 v210, v[156:159], s[6:7]
	s_waitcnt vmcnt(18)
	v_permlane16_swap_b32_e32 v132, v134
	v_permlane16_swap_b32_e32 v133, v135
	v_lshlrev_b32_e32 v156, 16, v128
	v_and_b32_e32 v157, 0xffff0000, v128
	v_lshlrev_b32_e32 v158, 16, v129
	v_and_b32_e32 v159, 0xffff0000, v129
	v_pk_mul_f32 v[156:157], v[36:37], v[156:157]
	v_pk_mul_f32 v[158:159], v[38:39], v[158:159]
	v_permlane32_swap_b32_e32 v132, v134
	v_permlane32_swap_b32_e32 v133, v135
	v_lshlrev_b32_e32 v244, 16, v130
	v_and_b32_e32 v245, 0xffff0000, v130
	v_lshlrev_b32_e32 v246, 16, v131
	v_and_b32_e32 v247, 0xffff0000, v131
	v_pk_mul_f32 v[244:245], v[32:33], v[244:245]
	v_pk_mul_f32 v[246:247], v[34:35], v[246:247]
	v_lshlrev_b32_e32 v196, 16, v132
	v_and_b32_e32 v197, 0xffff0000, v132
	v_lshlrev_b32_e32 v198, 16, v133
	v_and_b32_e32 v199, 0xffff0000, v133
	v_pk_add_f32 v[156:157], v[156:157], v[196:197]
	v_pk_add_f32 v[158:159], v[158:159], v[198:199]
	v_lshlrev_b32_e32 v200, 16, v134
	v_and_b32_e32 v201, 0xffff0000, v134
	v_lshlrev_b32_e32 v204, 16, v135
	v_and_b32_e32 v205, 0xffff0000, v135
	v_pk_add_f32 v[244:245], v[244:245], v[200:201]
	v_pk_add_f32 v[246:247], v[246:247], v[204:205]
	v_cvt_pk_bf16_f32 v156, v156, v157
	v_cvt_pk_bf16_f32 v157, v158, v159
	v_cvt_pk_bf16_f32 v158, v244, v245
	v_cvt_pk_bf16_f32 v159, v246, v247
	v_add_u32_e32 v211, 0xb0000, v163
	s_nop 1
	v_permlane32_swap_b32_e32 v156, v158
	v_permlane32_swap_b32_e32 v157, v159
	s_nop 0
	v_permlane16_swap_b32_e32 v156, v158
	v_permlane16_swap_b32_e32 v157, v159
	s_nop 1
	global_store_dwordx4 v211, v[156:159], s[6:7]
	s_waitcnt vmcnt(16)
	v_permlane16_swap_b32_e32 v140, v142
	v_permlane16_swap_b32_e32 v141, v143
	v_lshlrev_b32_e32 v156, 16, v136
	v_and_b32_e32 v157, 0xffff0000, v136
	v_lshlrev_b32_e32 v158, 16, v137
	v_and_b32_e32 v159, 0xffff0000, v137
	v_pk_mul_f32 v[156:157], v[28:29], v[156:157]
	v_pk_mul_f32 v[158:159], v[30:31], v[158:159]
	v_permlane32_swap_b32_e32 v140, v142
	v_permlane32_swap_b32_e32 v141, v143
	v_lshlrev_b32_e32 v244, 16, v138
	v_and_b32_e32 v245, 0xffff0000, v138
	v_lshlrev_b32_e32 v246, 16, v139
	v_and_b32_e32 v247, 0xffff0000, v139
	v_pk_mul_f32 v[244:245], v[24:25], v[244:245]
	v_pk_mul_f32 v[246:247], v[26:27], v[246:247]
	v_lshlrev_b32_e32 v196, 16, v140
	v_and_b32_e32 v197, 0xffff0000, v140
	v_lshlrev_b32_e32 v198, 16, v141
	v_and_b32_e32 v199, 0xffff0000, v141
	v_pk_add_f32 v[156:157], v[156:157], v[196:197]
	v_pk_add_f32 v[158:159], v[158:159], v[198:199]
	v_lshlrev_b32_e32 v200, 16, v142
	v_and_b32_e32 v201, 0xffff0000, v142
	v_lshlrev_b32_e32 v204, 16, v143
	v_and_b32_e32 v205, 0xffff0000, v143
	v_pk_add_f32 v[244:245], v[244:245], v[200:201]
	v_pk_add_f32 v[246:247], v[246:247], v[204:205]
	v_cvt_pk_bf16_f32 v156, v156, v157
	v_cvt_pk_bf16_f32 v157, v158, v159
	v_cvt_pk_bf16_f32 v158, v244, v245
	v_cvt_pk_bf16_f32 v159, v246, v247
	v_add_u32_e32 v210, 0x80000, v163
	s_nop 1
	v_permlane32_swap_b32_e32 v156, v158
	v_permlane32_swap_b32_e32 v157, v159
	s_nop 0
	v_permlane16_swap_b32_e32 v156, v158
	v_permlane16_swap_b32_e32 v157, v159
	s_nop 1
	global_store_dwordx4 v210, v[156:159], s[6:7] offset:256
	s_waitcnt vmcnt(14)
; __device__ __forceinline__ float bflo(unsigned u) { return __uint_as_float(u << 16); }
; __device__ __forceinline__ float bfhi(unsigned u) { return __uint_as_float(u & 0xFFFF0000u); }
; __device__ __forceinline__ void phaseE(const Params& p, int layer) {
;     ...
;               uint4 g4[2]; uint2 old[2][2];
; #pragma unroll
;               for (int mm = 0; mm < 2; mm++) {
;                 const int m = mh * 2 + mm;
;                 g4[mm] = *(const uint4*)(gsb + ((ai * 2 + bj) * 4 + m) * 8192 + gs_lane);
;                 if (br) {
; #pragma unroll
;                   for (int n = 0; n < 2; n++)
;                     old[mm][n] = *(const uint2*)(mb + ((size_t)(ai * 128 + m * 16) * 2048 + bj * 128 + n * 16) * 2 + lane_m);
;                 }
;               }
; #pragma unroll
;               for (int mm = 0; mm < 2; mm++) {
;                 const int m = mh * 2 + mm;
;                 const unsigned gq[4] = {g4[mm].x, g4[mm].y, g4[mm].z, g4[mm].w};
; #pragma unroll
;                 for (int n = 0; n < 2; n++) {
;                   f32x4 v = acc[ai][bj][m][n];
;                   float o0 = bflo(gq[2 * n]) * v[0], o1 = bfhi(gq[2 * n]) * v[1], o2 = bflo(gq[2 * n + 1]) * v[2], o3 = bfhi(gq[2 * n + 1]) * v[3];
;                   char* mp = mb + ((size_t)(ai * 128 + m * 16) * 2048 + bj * 128 + n * 16) * 2 + lane_m;
;                   if (br) { o0 += bflo(old[mm][n].x); o1 += bfhi(old[mm][n].x); o2 += bflo(old[mm][n].y); o3 += bfhi(old[mm][n].y); }
;                   *(uint2*)mp = make_uint2(pk2(o0, o1), pk2(o2, o3));
;                 }
;               }
	v_permlane16_swap_b32_e32 v152, v154
	v_permlane16_swap_b32_e32 v153, v155
	v_lshlrev_b32_e32 v156, 16, v148
	v_and_b32_e32 v157, 0xffff0000, v148
	v_lshlrev_b32_e32 v158, 16, v149
	v_and_b32_e32 v159, 0xffff0000, v149
	v_pk_mul_f32 v[156:157], v[20:21], v[156:157]
	v_pk_mul_f32 v[158:159], v[22:23], v[158:159]
	v_permlane32_swap_b32_e32 v152, v154
	v_permlane32_swap_b32_e32 v153, v155
	v_lshlrev_b32_e32 v244, 16, v150
	v_and_b32_e32 v245, 0xffff0000, v150
	v_lshlrev_b32_e32 v246, 16, v151
	v_and_b32_e32 v247, 0xffff0000, v151
	v_pk_mul_f32 v[244:245], v[16:17], v[244:245]
	v_pk_mul_f32 v[246:247], v[18:19], v[246:247]
	v_lshlrev_b32_e32 v196, 16, v152
	v_and_b32_e32 v197, 0xffff0000, v152
	v_lshlrev_b32_e32 v198, 16, v153
	v_and_b32_e32 v199, 0xffff0000, v153
	v_pk_add_f32 v[156:157], v[156:157], v[196:197]
	v_pk_add_f32 v[158:159], v[158:159], v[198:199]
	v_lshlrev_b32_e32 v200, 16, v154
	v_and_b32_e32 v201, 0xffff0000, v154
	v_lshlrev_b32_e32 v204, 16, v155
	v_and_b32_e32 v205, 0xffff0000, v155
	v_pk_add_f32 v[244:245], v[244:245], v[200:201]
	v_pk_add_f32 v[246:247], v[246:247], v[204:205]
	v_cvt_pk_bf16_f32 v156, v156, v157
	v_cvt_pk_bf16_f32 v157, v158, v159
	v_cvt_pk_bf16_f32 v158, v244, v245
	v_cvt_pk_bf16_f32 v159, v246, v247
	v_add_u32_e32 v211, 0x90000, v163
	s_nop 1
	v_permlane32_swap_b32_e32 v156, v158
	v_permlane32_swap_b32_e32 v157, v159
	s_nop 0
	v_permlane16_swap_b32_e32 v156, v158
	v_permlane16_swap_b32_e32 v157, v159
	s_nop 1
	global_store_dwordx4 v211, v[156:159], s[6:7] offset:256
	s_waitcnt vmcnt(12)
	v_permlane16_swap_b32_e32 v168, v170
	v_permlane16_swap_b32_e32 v169, v171
	v_lshlrev_b32_e32 v156, 16, v164
	v_and_b32_e32 v157, 0xffff0000, v164
	v_lshlrev_b32_e32 v158, 16, v165
	v_and_b32_e32 v159, 0xffff0000, v165
	v_pk_mul_f32 v[156:157], v[12:13], v[156:157]
	v_pk_mul_f32 v[158:159], v[14:15], v[158:159]
	v_permlane32_swap_b32_e32 v168, v170
	v_permlane32_swap_b32_e32 v169, v171
	v_lshlrev_b32_e32 v244, 16, v166
	v_and_b32_e32 v245, 0xffff0000, v166
	v_lshlrev_b32_e32 v246, 16, v167
	v_and_b32_e32 v247, 0xffff0000, v167
	v_pk_mul_f32 v[244:245], v[8:9], v[244:245]
	v_pk_mul_f32 v[246:247], v[10:11], v[246:247]
	v_lshlrev_b32_e32 v196, 16, v168
	v_and_b32_e32 v197, 0xffff0000, v168
	v_lshlrev_b32_e32 v198, 16, v169
	v_and_b32_e32 v199, 0xffff0000, v169
	v_pk_add_f32 v[156:157], v[156:157], v[196:197]
	v_pk_add_f32 v[158:159], v[158:159], v[198:199]
	v_lshlrev_b32_e32 v200, 16, v170
	v_and_b32_e32 v201, 0xffff0000, v170
	v_lshlrev_b32_e32 v204, 16, v171
	v_and_b32_e32 v205, 0xffff0000, v171
	v_pk_add_f32 v[244:245], v[244:245], v[200:201]
	v_pk_add_f32 v[246:247], v[246:247], v[204:205]
	v_cvt_pk_bf16_f32 v156, v156, v157
	v_cvt_pk_bf16_f32 v157, v158, v159
	v_cvt_pk_bf16_f32 v158, v244, v245
	v_cvt_pk_bf16_f32 v159, v246, v247
	v_add_u32_e32 v210, 0xa0000, v163
	s_nop 1
	v_permlane32_swap_b32_e32 v156, v158
	v_permlane32_swap_b32_e32 v157, v159
	s_nop 0
	v_permlane16_swap_b32_e32 v156, v158
	v_permlane16_swap_b32_e32 v157, v159
	s_nop 1
	global_store_dwordx4 v210, v[156:159], s[6:7] offset:256
	s_waitcnt vmcnt(10)
	v_permlane16_swap_b32_e32 v176, v178
	v_permlane16_swap_b32_e32 v177, v179
	v_lshlrev_b32_e32 v156, 16, v172
	v_and_b32_e32 v157, 0xffff0000, v172
	v_lshlrev_b32_e32 v158, 16, v173
	v_and_b32_e32 v159, 0xffff0000, v173
	v_pk_mul_f32 v[156:157], v[4:5], v[156:157]
	v_pk_mul_f32 v[158:159], v[6:7], v[158:159]
	v_permlane32_swap_b32_e32 v176, v178
	v_permlane32_swap_b32_e32 v177, v179
	v_lshlrev_b32_e32 v244, 16, v174
	v_and_b32_e32 v245, 0xffff0000, v174
	v_lshlrev_b32_e32 v246, 16, v175
	v_and_b32_e32 v247, 0xffff0000, v175
	v_pk_mul_f32 v[244:245], v[0:1], v[244:245]
	v_pk_mul_f32 v[246:247], v[2:3], v[246:247]
	v_lshlrev_b32_e32 v196, 16, v176
	v_and_b32_e32 v197, 0xffff0000, v176
	v_lshlrev_b32_e32 v198, 16, v177
	v_and_b32_e32 v199, 0xffff0000, v177
	v_pk_add_f32 v[156:157], v[156:157], v[196:197]
	v_pk_add_f32 v[158:159], v[158:159], v[198:199]
	v_lshlrev_b32_e32 v200, 16, v178
	v_and_b32_e32 v201, 0xffff0000, v178
	v_lshlrev_b32_e32 v204, 16, v179
	v_and_b32_e32 v205, 0xffff0000, v179
	v_pk_add_f32 v[244:245], v[244:245], v[200:201]
	v_pk_add_f32 v[246:247], v[246:247], v[204:205]
	v_cvt_pk_bf16_f32 v156, v156, v157
	v_cvt_pk_bf16_f32 v157, v158, v159
	v_cvt_pk_bf16_f32 v158, v244, v245
	v_cvt_pk_bf16_f32 v159, v246, v247
	v_add_u32_e32 v211, 0xb0000, v163
	s_nop 1
	v_permlane32_swap_b32_e32 v156, v158
	v_permlane32_swap_b32_e32 v157, v159
	s_nop 0
	v_permlane16_swap_b32_e32 v156, v158
	v_permlane16_swap_b32_e32 v157, v159
	s_nop 1
	global_store_dwordx4 v211, v[156:159], s[6:7] offset:256
	s_branch .LBB0_2313
; __device__ __forceinline__ float bflo(unsigned u) { return __uint_as_float(u << 16); }
; __device__ __forceinline__ float bfhi(unsigned u) { return __uint_as_float(u & 0xFFFF0000u); }
; __device__ __forceinline__ void phaseE(const Params& p, int layer) {
;     ...
;               uint4 g4[2]; uint2 old[2][2];
; #pragma unroll
;               for (int mm = 0; mm < 2; mm++) {
;                 const int m = mh * 2 + mm;
;                 g4[mm] = *(const uint4*)(gsb + ((ai * 2 + bj) * 4 + m) * 8192 + gs_lane);
;                 if (br) {
; #pragma unroll
;                   for (int n = 0; n < 2; n++)
;                     old[mm][n] = *(const uint2*)(mb + ((size_t)(ai * 128 + m * 16) * 2048 + bj * 128 + n * 16) * 2 + lane_m);
;                 }
;               }
; #pragma unroll
;               for (int mm = 0; mm < 2; mm++) {
;                 const int m = mh * 2 + mm;
;                 const unsigned gq[4] = {g4[mm].x, g4[mm].y, g4[mm].z, g4[mm].w};
; #pragma unroll
;                 for (int n = 0; n < 2; n++) {
;                   f32x4 v = acc[ai][bj][m][n];
;                   float o0 = bflo(gq[2 * n]) * v[0], o1 = bfhi(gq[2 * n]) * v[1], o2 = bflo(gq[2 * n + 1]) * v[2], o3 = bfhi(gq[2 * n + 1]) * v[3];
;                   char* mp = mb + ((size_t)(ai * 128 + m * 16) * 2048 + bj * 128 + n * 16) * 2 + lane_m;
;                   if (br) { o0 += bflo(old[mm][n].x); o1 += bfhi(old[mm][n].x); o2 += bflo(old[mm][n].y); o3 += bfhi(old[mm][n].y); }
;                   *(uint2*)mp = make_uint2(pk2(o0, o1), pk2(o2, o3));
;                 }
;               }
.Lbrepi_first:
	ds_read_b128 v[128:131], v165
	ds_read_b128 v[136:139], v165 offset:8192
	ds_read_b128 v[148:151], v165 offset:16384
	ds_read_b128 v[164:167], v165 offset:24576
	v_add_u32_e32 v146, 0x8000, v160
	global_load_dwordx4 v[172:175], v146, s[0:1]
	v_add_u32_e32 v147, 0xa000, v160
	global_load_dwordx4 v[180:183], v147, s[0:1]
	v_add_u32_e32 v146, 0xc000, v160
	global_load_dwordx4 v[188:191], v146, s[0:1]
	v_add_u32_e32 v147, 0xe000, v160
	global_load_dwordx4 v[212:215], v147, s[0:1]
	v_add_u32_e32 v146, 0x10000, v160
	global_load_dwordx4 v[220:223], v146, s[0:1]
	v_add_u32_e32 v147, 0x12000, v160
	global_load_dwordx4 v[228:231], v147, s[0:1]
	v_add_u32_e32 v146, 0x14000, v160
	global_load_dwordx4 v[236:239], v146, s[0:1]
	s_waitcnt lgkmcnt(0)
	v_lshlrev_b32_e32 v156, 16, v128
	v_and_b32_e32 v157, 0xffff0000, v128
	v_lshlrev_b32_e32 v158, 16, v129
	v_and_b32_e32 v159, 0xffff0000, v129
	v_pk_mul_f32 v[156:157], v[124:125], v[156:157]
	v_pk_mul_f32 v[158:159], v[126:127], v[158:159]
	v_lshlrev_b32_e32 v244, 16, v130
	v_and_b32_e32 v245, 0xffff0000, v130
	v_lshlrev_b32_e32 v246, 16, v131
	v_and_b32_e32 v247, 0xffff0000, v131
	v_pk_mul_f32 v[244:245], v[120:121], v[244:245]
	v_pk_mul_f32 v[246:247], v[122:123], v[246:247]
	v_cvt_pk_bf16_f32 v156, v156, v157
	v_cvt_pk_bf16_f32 v157, v158, v159
	v_cvt_pk_bf16_f32 v158, v244, v245
	v_cvt_pk_bf16_f32 v159, v246, v247
	s_nop 1
	v_permlane32_swap_b32_e32 v156, v158
	v_permlane32_swap_b32_e32 v157, v159
	s_nop 0
	v_permlane16_swap_b32_e32 v156, v158
	v_permlane16_swap_b32_e32 v157, v159
	s_nop 1
	global_store_dwordx4 v163, v[156:159], s[6:7]
	v_add_u32_e32 v147, 0x16000, v160
	global_load_dwordx4 v[128:131], v147, s[0:1]
	s_waitcnt lgkmcnt(0)
	v_lshlrev_b32_e32 v156, 16, v136
	v_and_b32_e32 v157, 0xffff0000, v136
	v_lshlrev_b32_e32 v158, 16, v137
	v_and_b32_e32 v159, 0xffff0000, v137
	v_pk_mul_f32 v[156:157], v[116:117], v[156:157]
	v_pk_mul_f32 v[158:159], v[118:119], v[158:159]
	v_lshlrev_b32_e32 v244, 16, v138
	v_and_b32_e32 v245, 0xffff0000, v138
	v_lshlrev_b32_e32 v246, 16, v139
	v_and_b32_e32 v247, 0xffff0000, v139
	v_pk_mul_f32 v[244:245], v[112:113], v[244:245]
	v_pk_mul_f32 v[246:247], v[114:115], v[246:247]
	v_cvt_pk_bf16_f32 v156, v156, v157
	v_cvt_pk_bf16_f32 v157, v158, v159
	v_cvt_pk_bf16_f32 v158, v244, v245
	v_cvt_pk_bf16_f32 v159, v246, v247
	v_add_u32_e32 v210, 0x10000, v163
	s_nop 1
	v_permlane32_swap_b32_e32 v156, v158
	v_permlane32_swap_b32_e32 v157, v159
	s_nop 0
	v_permlane16_swap_b32_e32 v156, v158
	v_permlane16_swap_b32_e32 v157, v159
	s_nop 1
	global_store_dwordx4 v210, v[156:159], s[6:7]
	v_add_u32_e32 v146, 0x18000, v160
	global_load_dwordx4 v[136:139], v146, s[0:1]
	s_waitcnt lgkmcnt(0)
	v_lshlrev_b32_e32 v156, 16, v148
	v_and_b32_e32 v157, 0xffff0000, v148
	v_lshlrev_b32_e32 v158, 16, v149
	v_and_b32_e32 v159, 0xffff0000, v149
	v_pk_mul_f32 v[156:157], v[108:109], v[156:157]
	v_pk_mul_f32 v[158:159], v[110:111], v[158:159]
	v_lshlrev_b32_e32 v244, 16, v150
	v_and_b32_e32 v245, 0xffff0000, v150
	v_lshlrev_b32_e32 v246, 16, v151
	v_and_b32_e32 v247, 0xffff0000, v151
	v_pk_mul_f32 v[244:245], v[104:105], v[244:245]
	v_pk_mul_f32 v[246:247], v[106:107], v[246:247]
	v_cvt_pk_bf16_f32 v156, v156, v157
	v_cvt_pk_bf16_f32 v157, v158, v159
	v_cvt_pk_bf16_f32 v158, v244, v245
	v_cvt_pk_bf16_f32 v159, v246, v247
	v_add_u32_e32 v211, 0x20000, v163
	s_nop 1
	v_permlane32_swap_b32_e32 v156, v158
	v_permlane32_swap_b32_e32 v157, v159
	s_nop 0
	v_permlane16_swap_b32_e32 v156, v158
	v_permlane16_swap_b32_e32 v157, v159
	s_nop 1
	global_store_dwordx4 v211, v[156:159], s[6:7]
	v_add_u32_e32 v147, 0x1a000, v160
	global_load_dwordx4 v[148:151], v147, s[0:1]
	s_waitcnt lgkmcnt(0)
	v_lshlrev_b32_e32 v156, 16, v164
	v_and_b32_e32 v157, 0xffff0000, v164
	v_lshlrev_b32_e32 v158, 16, v165
	v_and_b32_e32 v159, 0xffff0000, v165
	v_pk_mul_f32 v[156:157], v[100:101], v[156:157]
	v_pk_mul_f32 v[158:159], v[102:103], v[158:159]
	v_lshlrev_b32_e32 v244, 16, v166
	v_and_b32_e32 v245, 0xffff0000, v166
	v_lshlrev_b32_e32 v246, 16, v167
	v_and_b32_e32 v247, 0xffff0000, v167
	v_pk_mul_f32 v[244:245], v[96:97], v[244:245]
	v_pk_mul_f32 v[246:247], v[98:99], v[246:247]
	v_cvt_pk_bf16_f32 v156, v156, v157
	v_cvt_pk_bf16_f32 v157, v158, v159
	v_cvt_pk_bf16_f32 v158, v244, v245
	v_cvt_pk_bf16_f32 v159, v246, v247
	v_add_u32_e32 v210, 0x30000, v163
	s_nop 1
	v_permlane32_swap_b32_e32 v156, v158
	v_permlane32_swap_b32_e32 v157, v159
	s_nop 0
	v_permlane16_swap_b32_e32 v156, v158
	v_permlane16_swap_b32_e32 v157, v159
	s_nop 1
	global_store_dwordx4 v210, v[156:159], s[6:7]
	v_add_u32_e32 v146, 0x1c000, v160
	global_load_dwordx4 v[164:167], v146, s[0:1]
	s_waitcnt vmcnt(14)
	v_lshlrev_b32_e32 v156, 16, v172
	v_and_b32_e32 v157, 0xffff0000, v172
	v_lshlrev_b32_e32 v158, 16, v173
	v_and_b32_e32 v159, 0xffff0000, v173
	v_pk_mul_f32 v[156:157], v[92:93], v[156:157]
	v_pk_mul_f32 v[158:159], v[94:95], v[158:159]
	v_lshlrev_b32_e32 v244, 16, v174
	v_and_b32_e32 v245, 0xffff0000, v174
	v_lshlrev_b32_e32 v246, 16, v175
	v_and_b32_e32 v247, 0xffff0000, v175
	v_pk_mul_f32 v[244:245], v[88:89], v[244:245]
	v_pk_mul_f32 v[246:247], v[90:91], v[246:247]
	v_cvt_pk_bf16_f32 v156, v156, v157
	v_cvt_pk_bf16_f32 v157, v158, v159
	v_cvt_pk_bf16_f32 v158, v244, v245
	v_cvt_pk_bf16_f32 v159, v246, v247
	s_nop 1
	v_permlane32_swap_b32_e32 v156, v158
	v_permlane32_swap_b32_e32 v157, v159
	s_nop 0
	v_permlane16_swap_b32_e32 v156, v158
	v_permlane16_swap_b32_e32 v157, v159
	s_nop 1
	global_store_dwordx4 v163, v[156:159], s[6:7] offset:256
	v_add_u32_e32 v147, 0x1e000, v160
	global_load_dwordx4 v[172:175], v147, s[0:1]
	s_waitcnt vmcnt(15)
; __device__ __forceinline__ float bflo(unsigned u) { return __uint_as_float(u << 16); }
; __device__ __forceinline__ float bfhi(unsigned u) { return __uint_as_float(u & 0xFFFF0000u); }
; __device__ __forceinline__ void phaseE(const Params& p, int layer) {
;     ...
;               uint4 g4[2]; uint2 old[2][2];
; #pragma unroll
;               for (int mm = 0; mm < 2; mm++) {
;                 const int m = mh * 2 + mm;
;                 g4[mm] = *(const uint4*)(gsb + ((ai * 2 + bj) * 4 + m) * 8192 + gs_lane);
;                 if (br) {
; #pragma unroll
;                   for (int n = 0; n < 2; n++)
;                     old[mm][n] = *(const uint2*)(mb + ((size_t)(ai * 128 + m * 16) * 2048 + bj * 128 + n * 16) * 2 + lane_m);
;                 }
;               }
; #pragma unroll
;               for (int mm = 0; mm < 2; mm++) {
;                 const int m = mh * 2 + mm;
;                 const unsigned gq[4] = {g4[mm].x, g4[mm].y, g4[mm].z, g4[mm].w};
; #pragma unroll
;                 for (int n = 0; n < 2; n++) {
;                   f32x4 v = acc[ai][bj][m][n];
;                   float o0 = bflo(gq[2 * n]) * v[0], o1 = bfhi(gq[2 * n]) * v[1], o2 = bflo(gq[2 * n + 1]) * v[2], o3 = bfhi(gq[2 * n + 1]) * v[3];
;                   char* mp = mb + ((size_t)(ai * 128 + m * 16) * 2048 + bj * 128 + n * 16) * 2 + lane_m;
;                   if (br) { o0 += bflo(old[mm][n].x); o1 += bfhi(old[mm][n].x); o2 += bflo(old[mm][n].y); o3 += bfhi(old[mm][n].y); }
;                   *(uint2*)mp = make_uint2(pk2(o0, o1), pk2(o2, o3));
;                 }
;               }
	v_lshlrev_b32_e32 v156, 16, v180
	v_and_b32_e32 v157, 0xffff0000, v180
	v_lshlrev_b32_e32 v158, 16, v181
	v_and_b32_e32 v159, 0xffff0000, v181
	v_pk_mul_f32 v[156:157], v[84:85], v[156:157]
	v_pk_mul_f32 v[158:159], v[86:87], v[158:159]
	v_lshlrev_b32_e32 v244, 16, v182
	v_and_b32_e32 v245, 0xffff0000, v182
	v_lshlrev_b32_e32 v246, 16, v183
	v_and_b32_e32 v247, 0xffff0000, v183
	v_pk_mul_f32 v[244:245], v[80:81], v[244:245]
	v_pk_mul_f32 v[246:247], v[82:83], v[246:247]
	v_cvt_pk_bf16_f32 v156, v156, v157
	v_cvt_pk_bf16_f32 v157, v158, v159
	v_cvt_pk_bf16_f32 v158, v244, v245
	v_cvt_pk_bf16_f32 v159, v246, v247
	v_add_u32_e32 v211, 0x10000, v163
	s_nop 1
	v_permlane32_swap_b32_e32 v156, v158
	v_permlane32_swap_b32_e32 v157, v159
	s_nop 0
	v_permlane16_swap_b32_e32 v156, v158
	v_permlane16_swap_b32_e32 v157, v159
	s_nop 1
	global_store_dwordx4 v211, v[156:159], s[6:7] offset:256
	s_waitcnt vmcnt(15)
	v_lshlrev_b32_e32 v156, 16, v188
	v_and_b32_e32 v157, 0xffff0000, v188
	v_lshlrev_b32_e32 v158, 16, v189
	v_and_b32_e32 v159, 0xffff0000, v189
	v_pk_mul_f32 v[156:157], v[76:77], v[156:157]
	v_pk_mul_f32 v[158:159], v[78:79], v[158:159]
	v_lshlrev_b32_e32 v244, 16, v190
	v_and_b32_e32 v245, 0xffff0000, v190
	v_lshlrev_b32_e32 v246, 16, v191
	v_and_b32_e32 v247, 0xffff0000, v191
	v_pk_mul_f32 v[244:245], v[72:73], v[244:245]
	v_pk_mul_f32 v[246:247], v[74:75], v[246:247]
	v_cvt_pk_bf16_f32 v156, v156, v157
	v_cvt_pk_bf16_f32 v157, v158, v159
	v_cvt_pk_bf16_f32 v158, v244, v245
	v_cvt_pk_bf16_f32 v159, v246, v247
	v_add_u32_e32 v210, 0x20000, v163
	s_nop 1
	v_permlane32_swap_b32_e32 v156, v158
	v_permlane32_swap_b32_e32 v157, v159
	s_nop 0
	v_permlane16_swap_b32_e32 v156, v158
	v_permlane16_swap_b32_e32 v157, v159
	s_nop 1
	global_store_dwordx4 v210, v[156:159], s[6:7] offset:256
	s_waitcnt vmcnt(15)
	v_lshlrev_b32_e32 v156, 16, v212
	v_and_b32_e32 v157, 0xffff0000, v212
	v_lshlrev_b32_e32 v158, 16, v213
	v_and_b32_e32 v159, 0xffff0000, v213
	v_pk_mul_f32 v[156:157], v[68:69], v[156:157]
	v_pk_mul_f32 v[158:159], v[70:71], v[158:159]
	v_lshlrev_b32_e32 v244, 16, v214
	v_and_b32_e32 v245, 0xffff0000, v214
	v_lshlrev_b32_e32 v246, 16, v215
	v_and_b32_e32 v247, 0xffff0000, v215
	v_pk_mul_f32 v[244:245], v[64:65], v[244:245]
	v_pk_mul_f32 v[246:247], v[66:67], v[246:247]
	v_cvt_pk_bf16_f32 v156, v156, v157
	v_cvt_pk_bf16_f32 v157, v158, v159
	v_cvt_pk_bf16_f32 v158, v244, v245
	v_cvt_pk_bf16_f32 v159, v246, v247
	v_add_u32_e32 v211, 0x30000, v163
	s_nop 1
	v_permlane32_swap_b32_e32 v156, v158
	v_permlane32_swap_b32_e32 v157, v159
	s_nop 0
	v_permlane16_swap_b32_e32 v156, v158
	v_permlane16_swap_b32_e32 v157, v159
	s_nop 1
	global_store_dwordx4 v211, v[156:159], s[6:7] offset:256
	s_waitcnt vmcnt(15)
	v_lshlrev_b32_e32 v156, 16, v220
	v_and_b32_e32 v157, 0xffff0000, v220
	v_lshlrev_b32_e32 v158, 16, v221
	v_and_b32_e32 v159, 0xffff0000, v221
	v_pk_mul_f32 v[156:157], v[60:61], v[156:157]
	v_pk_mul_f32 v[158:159], v[62:63], v[158:159]
	v_lshlrev_b32_e32 v244, 16, v222
	v_and_b32_e32 v245, 0xffff0000, v222
	v_lshlrev_b32_e32 v246, 16, v223
	v_and_b32_e32 v247, 0xffff0000, v223
	v_pk_mul_f32 v[244:245], v[56:57], v[244:245]
	v_pk_mul_f32 v[246:247], v[58:59], v[246:247]
	v_cvt_pk_bf16_f32 v156, v156, v157
	v_cvt_pk_bf16_f32 v157, v158, v159
	v_cvt_pk_bf16_f32 v158, v244, v245
	v_cvt_pk_bf16_f32 v159, v246, v247
	v_add_u32_e32 v210, 0x80000, v163
	s_nop 1
	v_permlane32_swap_b32_e32 v156, v158
	v_permlane32_swap_b32_e32 v157, v159
	s_nop 0
	v_permlane16_swap_b32_e32 v156, v158
	v_permlane16_swap_b32_e32 v157, v159
	s_nop 1
	global_store_dwordx4 v210, v[156:159], s[6:7]
	s_waitcnt vmcnt(15)
	v_lshlrev_b32_e32 v156, 16, v228
	v_and_b32_e32 v157, 0xffff0000, v228
	v_lshlrev_b32_e32 v158, 16, v229
	v_and_b32_e32 v159, 0xffff0000, v229
	v_pk_mul_f32 v[156:157], v[52:53], v[156:157]
	v_pk_mul_f32 v[158:159], v[54:55], v[158:159]
	v_lshlrev_b32_e32 v244, 16, v230
	v_and_b32_e32 v245, 0xffff0000, v230
	v_lshlrev_b32_e32 v246, 16, v231
	v_and_b32_e32 v247, 0xffff0000, v231
	v_pk_mul_f32 v[244:245], v[48:49], v[244:245]
	v_pk_mul_f32 v[246:247], v[50:51], v[246:247]
	v_cvt_pk_bf16_f32 v156, v156, v157
	v_cvt_pk_bf16_f32 v157, v158, v159
	v_cvt_pk_bf16_f32 v158, v244, v245
	v_cvt_pk_bf16_f32 v159, v246, v247
	v_add_u32_e32 v211, 0x90000, v163
	s_nop 1
	v_permlane32_swap_b32_e32 v156, v158
	v_permlane32_swap_b32_e32 v157, v159
	s_nop 0
	v_permlane16_swap_b32_e32 v156, v158
	v_permlane16_swap_b32_e32 v157, v159
	s_nop 1
	global_store_dwordx4 v211, v[156:159], s[6:7]
	s_waitcnt vmcnt(15)
; __device__ __forceinline__ float bflo(unsigned u) { return __uint_as_float(u << 16); }
; __device__ __forceinline__ float bfhi(unsigned u) { return __uint_as_float(u & 0xFFFF0000u); }
; __device__ __forceinline__ void phaseE(const Params& p, int layer) {
;     ...
;               uint4 g4[2]; uint2 old[2][2];
; #pragma unroll
;               for (int mm = 0; mm < 2; mm++) {
;                 const int m = mh * 2 + mm;
;                 g4[mm] = *(const uint4*)(gsb + ((ai * 2 + bj) * 4 + m) * 8192 + gs_lane);
;                 if (br) {
; #pragma unroll
;                   for (int n = 0; n < 2; n++)
;                     old[mm][n] = *(const uint2*)(mb + ((size_t)(ai * 128 + m * 16) * 2048 + bj * 128 + n * 16) * 2 + lane_m);
;                 }
;               }
; #pragma unroll
;               for (int mm = 0; mm < 2; mm++) {
;                 const int m = mh * 2 + mm;
;                 const unsigned gq[4] = {g4[mm].x, g4[mm].y, g4[mm].z, g4[mm].w};
; #pragma unroll
;                 for (int n = 0; n < 2; n++) {
;                   f32x4 v = acc[ai][bj][m][n];
;                   float o0 = bflo(gq[2 * n]) * v[0], o1 = bfhi(gq[2 * n]) * v[1], o2 = bflo(gq[2 * n + 1]) * v[2], o3 = bfhi(gq[2 * n + 1]) * v[3];
;                   char* mp = mb + ((size_t)(ai * 128 + m * 16) * 2048 + bj * 128 + n * 16) * 2 + lane_m;
;                   if (br) { o0 += bflo(old[mm][n].x); o1 += bfhi(old[mm][n].x); o2 += bflo(old[mm][n].y); o3 += bfhi(old[mm][n].y); }
;                   *(uint2*)mp = make_uint2(pk2(o0, o1), pk2(o2, o3));
;                 }
;               }
	v_lshlrev_b32_e32 v156, 16, v236
	v_and_b32_e32 v157, 0xffff0000, v236
	v_lshlrev_b32_e32 v158, 16, v237
	v_and_b32_e32 v159, 0xffff0000, v237
	v_pk_mul_f32 v[156:157], v[44:45], v[156:157]
	v_pk_mul_f32 v[158:159], v[46:47], v[158:159]
	v_lshlrev_b32_e32 v244, 16, v238
	v_and_b32_e32 v245, 0xffff0000, v238
	v_lshlrev_b32_e32 v246, 16, v239
	v_and_b32_e32 v247, 0xffff0000, v239
	v_pk_mul_f32 v[244:245], v[40:41], v[244:245]
	v_pk_mul_f32 v[246:247], v[42:43], v[246:247]
	v_cvt_pk_bf16_f32 v156, v156, v157
	v_cvt_pk_bf16_f32 v157, v158, v159
	v_cvt_pk_bf16_f32 v158, v244, v245
	v_cvt_pk_bf16_f32 v159, v246, v247
	v_add_u32_e32 v210, 0xa0000, v163
	s_nop 1
	v_permlane32_swap_b32_e32 v156, v158
	v_permlane32_swap_b32_e32 v157, v159
	s_nop 0
	v_permlane16_swap_b32_e32 v156, v158
	v_permlane16_swap_b32_e32 v157, v159
	s_nop 1
	global_store_dwordx4 v210, v[156:159], s[6:7]
	s_waitcnt vmcnt(14)
	v_lshlrev_b32_e32 v156, 16, v128
	v_and_b32_e32 v157, 0xffff0000, v128
	v_lshlrev_b32_e32 v158, 16, v129
	v_and_b32_e32 v159, 0xffff0000, v129
	v_pk_mul_f32 v[156:157], v[36:37], v[156:157]
	v_pk_mul_f32 v[158:159], v[38:39], v[158:159]
	v_lshlrev_b32_e32 v244, 16, v130
	v_and_b32_e32 v245, 0xffff0000, v130
	v_lshlrev_b32_e32 v246, 16, v131
	v_and_b32_e32 v247, 0xffff0000, v131
	v_pk_mul_f32 v[244:245], v[32:33], v[244:245]
	v_pk_mul_f32 v[246:247], v[34:35], v[246:247]
	v_cvt_pk_bf16_f32 v156, v156, v157
	v_cvt_pk_bf16_f32 v157, v158, v159
	v_cvt_pk_bf16_f32 v158, v244, v245
	v_cvt_pk_bf16_f32 v159, v246, v247
	v_add_u32_e32 v211, 0xb0000, v163
	s_nop 1
	v_permlane32_swap_b32_e32 v156, v158
	v_permlane32_swap_b32_e32 v157, v159
	s_nop 0
	v_permlane16_swap_b32_e32 v156, v158
	v_permlane16_swap_b32_e32 v157, v159
	s_nop 1
	global_store_dwordx4 v211, v[156:159], s[6:7]
	s_waitcnt vmcnt(13)
	v_lshlrev_b32_e32 v156, 16, v136
	v_and_b32_e32 v157, 0xffff0000, v136
	v_lshlrev_b32_e32 v158, 16, v137
	v_and_b32_e32 v159, 0xffff0000, v137
	v_pk_mul_f32 v[156:157], v[28:29], v[156:157]
	v_pk_mul_f32 v[158:159], v[30:31], v[158:159]
	v_lshlrev_b32_e32 v244, 16, v138
	v_and_b32_e32 v245, 0xffff0000, v138
	v_lshlrev_b32_e32 v246, 16, v139
	v_and_b32_e32 v247, 0xffff0000, v139
	v_pk_mul_f32 v[244:245], v[24:25], v[244:245]
	v_pk_mul_f32 v[246:247], v[26:27], v[246:247]
	v_cvt_pk_bf16_f32 v156, v156, v157
	v_cvt_pk_bf16_f32 v157, v158, v159
	v_cvt_pk_bf16_f32 v158, v244, v245
	v_cvt_pk_bf16_f32 v159, v246, v247
	v_add_u32_e32 v210, 0x80000, v163
	s_nop 1
	v_permlane32_swap_b32_e32 v156, v158
	v_permlane32_swap_b32_e32 v157, v159
	s_nop 0
	v_permlane16_swap_b32_e32 v156, v158
	v_permlane16_swap_b32_e32 v157, v159
	s_nop 1
	global_store_dwordx4 v210, v[156:159], s[6:7] offset:256
	s_waitcnt vmcnt(12)
	v_lshlrev_b32_e32 v156, 16, v148
	v_and_b32_e32 v157, 0xffff0000, v148
	v_lshlrev_b32_e32 v158, 16, v149
	v_and_b32_e32 v159, 0xffff0000, v149
	v_pk_mul_f32 v[156:157], v[20:21], v[156:157]
	v_pk_mul_f32 v[158:159], v[22:23], v[158:159]
	v_lshlrev_b32_e32 v244, 16, v150
	v_and_b32_e32 v245, 0xffff0000, v150
	v_lshlrev_b32_e32 v246, 16, v151
	v_and_b32_e32 v247, 0xffff0000, v151
	v_pk_mul_f32 v[244:245], v[16:17], v[244:245]
	v_pk_mul_f32 v[246:247], v[18:19], v[246:247]
	v_cvt_pk_bf16_f32 v156, v156, v157
	v_cvt_pk_bf16_f32 v157, v158, v159
	v_cvt_pk_bf16_f32 v158, v244, v245
	v_cvt_pk_bf16_f32 v159, v246, v247
	v_add_u32_e32 v211, 0x90000, v163
	s_nop 1
	v_permlane32_swap_b32_e32 v156, v158
	v_permlane32_swap_b32_e32 v157, v159
	s_nop 0
	v_permlane16_swap_b32_e32 v156, v158
	v_permlane16_swap_b32_e32 v157, v159
	s_nop 1
	global_store_dwordx4 v211, v[156:159], s[6:7] offset:256
	s_waitcnt vmcnt(11)
	v_lshlrev_b32_e32 v156, 16, v164
	v_and_b32_e32 v157, 0xffff0000, v164
	v_lshlrev_b32_e32 v158, 16, v165
	v_and_b32_e32 v159, 0xffff0000, v165
	v_pk_mul_f32 v[156:157], v[12:13], v[156:157]
	v_pk_mul_f32 v[158:159], v[14:15], v[158:159]
	v_lshlrev_b32_e32 v244, 16, v166
	v_and_b32_e32 v245, 0xffff0000, v166
	v_lshlrev_b32_e32 v246, 16, v167
	v_and_b32_e32 v247, 0xffff0000, v167
	v_pk_mul_f32 v[244:245], v[8:9], v[244:245]
	v_pk_mul_f32 v[246:247], v[10:11], v[246:247]
	v_cvt_pk_bf16_f32 v156, v156, v157
	v_cvt_pk_bf16_f32 v157, v158, v159
	v_cvt_pk_bf16_f32 v158, v244, v245
	v_cvt_pk_bf16_f32 v159, v246, v247
	v_add_u32_e32 v210, 0xa0000, v163
	s_nop 1
	v_permlane32_swap_b32_e32 v156, v158
	v_permlane32_swap_b32_e32 v157, v159
	s_nop 0
	v_permlane16_swap_b32_e32 v156, v158
	v_permlane16_swap_b32_e32 v157, v159
	s_nop 1
	global_store_dwordx4 v210, v[156:159], s[6:7] offset:256
	s_waitcnt vmcnt(10)
	v_lshlrev_b32_e32 v156, 16, v172
	v_and_b32_e32 v157, 0xffff0000, v172
	v_lshlrev_b32_e32 v158, 16, v173
	v_and_b32_e32 v159, 0xffff0000, v173
	v_pk_mul_f32 v[156:157], v[4:5], v[156:157]
	v_pk_mul_f32 v[158:159], v[6:7], v[158:159]
	v_lshlrev_b32_e32 v244, 16, v174
	v_and_b32_e32 v245, 0xffff0000, v174
	v_lshlrev_b32_e32 v246, 16, v175
	v_and_b32_e32 v247, 0xffff0000, v175
	v_pk_mul_f32 v[244:245], v[0:1], v[244:245]
	v_pk_mul_f32 v[246:247], v[2:3], v[246:247]
	v_cvt_pk_bf16_f32 v156, v156, v157
	v_cvt_pk_bf16_f32 v157, v158, v159
	v_cvt_pk_bf16_f32 v158, v244, v245
	v_cvt_pk_bf16_f32 v159, v246, v247
	v_add_u32_e32 v211, 0xb0000, v163
	s_nop 1
	v_permlane32_swap_b32_e32 v156, v158
	v_permlane32_swap_b32_e32 v157, v159
	s_nop 0
	v_permlane16_swap_b32_e32 v156, v158
	v_permlane16_swap_b32_e32 v157, v159
	s_nop 1
	global_store_dwordx4 v211, v[156:159], s[6:7] offset:256
	s_branch .LBB0_2313
